# attention QK/PV: 14 LDS fragment reads in flight using dead VGPRs; ssm_prep km loop bounded by part; plus earlier prologue/scan/bias changes
# baseline (speedup 1.0000x reference)
; __device__ void ssm_prep(const Params& p, int g, int part, float* L) {
;   float* powr = L; float* powi = L + 17 * 64; float* bbr = L + 2 * 17 * 64; float* bbi = bbr + 1024; float* cr = bbi + 1024; float* ci = cr + 1024; float* km = ci + 1024;
;   const int tid = threadIdx.x;
;   const float dt = __expf(p.in[17][g]);
;   if (tid < 64) { const int pp = tid; const float lr = p.in[15][g * 64 + pp], li = p.in[16][g * 64 + pp];
;     ...
;   for (int i = tid; i < 4096; i += 512) { const int d = i >> 8, hp = (i >> 4) & 15, h = i & 15; float s = 0.f;
.LBB0_8:
	s_and_b32 s62, s61, 63
	s_lshr_b32 s98, s61, 6
	s_lshl_b32 s98, s98, 10
	s_add_u32 s98, s98, 0x1ff
	s_and_saveexec_b64 s[22:23], s[4:5]
	s_cbranch_execz .LBB0_16
	s_load_dwordx16 s[36:51], s[0:1], 0x80
	s_lshl_b32 s8, s62, 2
	v_mov_b32_e32 v2, s8
	s_load_dwordx16 s[68:83], s[0:1], 0x40
	v_lshl_or_b32 v6, s62, 6, v148
	s_waitcnt lgkmcnt(0)
	global_load_dword v2, v2, s[38:39]
	v_lshlrev_b32_e32 v5, 2, v6
	global_load_dword v4, v5, s[82:83]
	s_nop 0
	global_load_dword v5, v5, s[36:37]
	s_mov_b32 s63, 0
	v_mov_b32_e32 v27, v8
	s_waitcnt vmcnt(2)
	v_mul_f32_e32 v2, 0x3fb8aa3b, v2
	v_exp_f32_e32 v2, v2
	s_waitcnt vmcnt(1)
	v_mul_f32_e32 v7, v4, v2
	s_waitcnt vmcnt(0)
	v_mul_f32_e32 v26, v2, v5
	s_branch .LBB0_11

; __device__ void ssm_prep(const Params& p, int g, int part, float* L) {
;     ...
;   for (int i = tid; i < 4096; i += 512) { const int d = i >> 8, hp = (i >> 4) & 15, h = i & 15; float s = 0.f;
;     for (int pp = 0; pp < 64; ++pp) { const float c_r = cr[hp * 64 + pp], c_i = ci[hp * 64 + pp], pr = powr[d * 64 + pp], pi = powi[d * 64 + pp];
;       const float wr_ = c_r * pr - c_i * pi, wi_ = c_r * pi + c_i * pr; s += wr_ * bbr[pp * 16 + h] - wi_ * bbi[pp * 16 + h]; }
;     if (d == 0 && hp == h) s += p.in[22][g * 16 + h];
;     km[i] = s; }
.LBB0_19:
	s_or_b64 exec, exec, s[10:11]
	v_lshl_add_u32 v26, v6, 2, 0
	ds_write_b32 v26, v7 offset:25088
	v_add_u32_e32 v7, 0x200, v6
	v_cmp_lt_u32_e32 vcc, s98, v6
	v_add_u16_e32 v2, 2, v2
	s_or_b64 s[8:9], vcc, s[8:9]
	v_mov_b32_e32 v6, v7
	s_andn2_b64 exec, exec, s[8:9]
	s_cbranch_execz .LBB0_24

; #define LAS __attribute__((address_space(3)))
; #define MFMA16(a, b, c) __builtin_amdgcn_mfma_f32_16x16x32_bf16((a), (b), (c), 0, 0, 0)
; __device__ __forceinline__ void attn_wg_item(const Params& p, int item, LAS unsigned char* lds) {
;     ...
;     LAS unsigned char* Kl = lds + (ps & 1) * ATT_BUF + hh * ATT_TILE; LAS unsigned char* Vl = Kl + 2 * ATT_TILE;
;     f32x4 S[4];
; #pragma unroll
;     for (int kt = 0; kt < 4; ++kt) { f32x4 a = (f32x4){0.f, 0.f, 0.f, 0.f};
; #pragma unroll
;       for (int j = 0; j < 4; ++j) { const bf16x8 Kf = *(const LAS bf16x8*)(Kl + (16 * kt + l15) * 272 + 64 * j + 16 * kq); a = MFMA16(Kf, Qf[j], a); }
;       S[kt] = a; }
;     float tmax = -1e30f;
;     if (D0 + (qi & ~15) - (r0 + 63) >= 256 && r0 >= rmin) {
;       const float bc = bl[320];
; #pragma unroll
;       for (int kt = 0; kt < 4; ++kt)
; #pragma unroll
;         for (int i = 0; i < 4; ++i) { const float sv = S[kt][i] + bc; S[kt][i] = sv; tmax = fmaxf(tmax, sv); }
.LBB0_818:
	s_add_i32 s14, s18, s19
	s_bitcmp1_b32 s8, 0
	s_cselect_b32 s15, 0x11000, 0
	s_add_i32 s16, s38, s15
	v_add3_u32 v130, s16, v138, v141
	ds_read_b128 v[184:187], v130
	ds_read_b128 v[188:191], v130 offset:4352
	ds_read_b128 v[192:195], v130 offset:8704
	ds_read_b128 v[196:199], v130 offset:13056
	ds_read_b128 v[200:203], v130 offset:64
	ds_read_b128 v[204:207], v130 offset:4416
	ds_read_b128 v[208:211], v130 offset:8768
	ds_read_b128 v[212:215], v130 offset:13120
	ds_read_b128 v[216:219], v130 offset:128
	ds_read_b128 v[220:223], v130 offset:4480
	ds_read_b128 v[224:227], v130 offset:8832
	ds_read_b128 v[228:231], v130 offset:13184
	ds_read_b128 v[232:235], v130 offset:192
	ds_read_b128 v[236:239], v130 offset:4544
	s_cmp_ge_u32 s14, s34
	s_cselect_b64 s[14:15], -1, 0
	s_waitcnt lgkmcnt(13)
	v_mfma_f32_16x16x32_bf16 v[92:95], v[184:187], v[40:43], 0
	ds_read_b128 v[240:243], v130 offset:8896
	s_waitcnt lgkmcnt(13)
	v_mfma_f32_16x16x32_bf16 v[88:91], v[188:191], v[40:43], 0
	ds_read_b128 v[172:175], v130 offset:13248
	s_waitcnt lgkmcnt(13)
	v_mfma_f32_16x16x32_bf16 v[84:87], v[192:195], v[40:43], 0
	s_waitcnt lgkmcnt(12)
	v_mfma_f32_16x16x32_bf16 v[80:83], v[196:199], v[40:43], 0
	s_waitcnt lgkmcnt(11)
	v_mfma_f32_16x16x32_bf16 v[92:95], v[200:203], v[44:47], v[92:95]
	s_waitcnt lgkmcnt(10)
	v_mfma_f32_16x16x32_bf16 v[88:91], v[204:207], v[44:47], v[88:91]
	s_waitcnt lgkmcnt(9)
	v_mfma_f32_16x16x32_bf16 v[84:87], v[208:211], v[44:47], v[84:87]
	s_waitcnt lgkmcnt(8)
	v_mfma_f32_16x16x32_bf16 v[80:83], v[212:215], v[44:47], v[80:83]
	s_waitcnt lgkmcnt(7)
	v_mfma_f32_16x16x32_bf16 v[92:95], v[216:219], v[48:51], v[92:95]
	s_waitcnt lgkmcnt(6)
	v_mfma_f32_16x16x32_bf16 v[88:91], v[220:223], v[48:51], v[88:91]
	s_waitcnt lgkmcnt(5)
	v_mfma_f32_16x16x32_bf16 v[84:87], v[224:227], v[48:51], v[84:87]
	s_waitcnt lgkmcnt(4)
	v_mfma_f32_16x16x32_bf16 v[80:83], v[228:231], v[48:51], v[80:83]
	v_add_u32_e32 v122, s9, v107
	v_cmp_lt_i32_e32 vcc, s23, v122
	s_waitcnt lgkmcnt(3)
	v_mfma_f32_16x16x32_bf16 v[92:95], v[232:235], v[52:55], v[92:95]
	s_waitcnt lgkmcnt(2)
	v_mfma_f32_16x16x32_bf16 v[88:91], v[236:239], v[52:55], v[88:91]
	s_and_b64 s[14:15], s[14:15], vcc
	s_waitcnt lgkmcnt(1)
	v_mfma_f32_16x16x32_bf16 v[84:87], v[240:243], v[52:55], v[84:87]
	s_waitcnt lgkmcnt(0)
	v_mfma_f32_16x16x32_bf16 v[80:83], v[172:175], v[52:55], v[80:83]
	s_nop 7
	s_and_saveexec_b64 s[40:41], s[14:15]
	s_xor_b64 s[14:15], exec, s[40:41]
	s_cbranch_execz .LBB0_820
	v_mov_b32_e32 v122, s37
	ds_read_b32 v136, v122 offset:1280
	s_waitcnt lgkmcnt(0)
	v_pk_add_f32 v[122:123], v[92:93], v[136:137] op_sel_hi:[1,0]
	v_pk_add_f32 v[124:125], v[94:95], v[136:137] op_sel_hi:[1,0]
	v_pk_add_f32 v[130:131], v[84:85], v[136:137] op_sel_hi:[1,0]
	v_max_f32_e32 v84, 0xf149f2ca, v122
	v_pk_add_f32 v[126:127], v[88:89], v[136:137] op_sel_hi:[1,0]
	v_max3_f32 v84, v84, v123, v124
	v_pk_add_f32 v[128:129], v[90:91], v[136:137] op_sel_hi:[1,0]
	v_max3_f32 v84, v84, v125, v126
	v_max3_f32 v84, v84, v127, v128
	v_max3_f32 v84, v84, v129, v130
	v_pk_add_f32 v[132:133], v[86:87], v[136:137] op_sel_hi:[1,0]
	v_pk_add_f32 v[134:135], v[80:81], v[136:137] op_sel_hi:[1,0]
	v_max3_f32 v84, v84, v131, v132
	v_max3_f32 v84, v84, v133, v134
	v_add_f32_e32 v157, v82, v136
	v_max3_f32 v158, v84, v135, v157

; __device__ __forceinline__ unsigned cvt_pk_bf16(float lo, float hi) { unsigned r; asm("v_cvt_pk_bf16_f32 %0, %1, %2" : "=v"(r) : "v"(lo), "v"(hi)); return r; }
; #define LAS __attribute__((address_space(3)))
; #define MFMA16(a, b, c) __builtin_amdgcn_mfma_f32_16x16x32_bf16((a), (b), (c), 0, 0, 0)
; #define ATT_STORE(buf_) do { _Pragma("unroll") for (int i = 0; i < 8; ++i) \
;     *(LAS u32x4*)(st0 + (buf_) * ATT_BUF + ((i >> 2) * 2 + ((i >> 1) & 1)) * ATT_TILE + (i & 1) * 32 * 272) = t[i]; } while (0)
; __device__ __forceinline__ void attn_wg_item(const Params& p, int item, LAS unsigned char* lds) {
;     ...
;     tmax = fmaxf(tmax, __shfl_xor(tmax, 16)); tmax = fmaxf(tmax, __shfl_xor(tmax, 32));
;     const float mnew = fmaxf(mrun, tmax), alpha = __builtin_amdgcn_exp2f(mrun - mnew); mrun = mnew;
;     float psum = 0.f;
; #pragma unroll
;     for (int kt = 0; kt < 4; ++kt)
; #pragma unroll
;       for (int i = 0; i < 4; ++i) { const float e = __builtin_amdgcn_exp2f(S[kt][i] - mnew); S[kt][i] = e; psum += e; }
;     lsum = lsum * alpha + psum;
; #pragma unroll
;     for (int dt = 0; dt < 8; ++dt) O[dt] *= alpha;
;     bf16x8 Pf[2];
; #pragma unroll
;     for (int s2 = 0; s2 < 2; ++s2) { u32x4 wv; wv.x = cvt_pk_bf16(S[2 * s2][0], S[2 * s2][1]); wv.y = cvt_pk_bf16(S[2 * s2][2], S[2 * s2][3]);
;       wv.z = cvt_pk_bf16(S[2 * s2 + 1][0], S[2 * s2 + 1][1]); wv.w = cvt_pk_bf16(S[2 * s2 + 1][2], S[2 * s2 + 1][3]); Pf[s2] = __builtin_bit_cast(bf16x8, wv); }
;     { const int qq = l15 >> 2, pp = l15 & 3; LAS unsigned char* vb = Vl + (4 * kq + qq) * 272 + pp * 8;
; #pragma unroll
;       for (int s2 = 0; s2 < 2; ++s2)
; #pragma unroll
;         for (int dt = 0; dt < 8; ++dt) {
;           const s16x4 lo = __builtin_amdgcn_ds_read_tr16_b64_v4i16((LAS s16x4*)(vb + (32 * s2) * 272 + dt * 32));
;           const s16x4 hi = __builtin_amdgcn_ds_read_tr16_b64_v4i16((LAS s16x4*)(vb + (32 * s2 + 16) * 272 + dt * 32));
;           const bf16x8 Vf = __builtin_shufflevector(lo, hi, 0, 1, 2, 3, 4, 5, 6, 7);
;           O[dt] = MFMA16(Vf, Pf[s2], O[dt]); } }
;     if (ps < 8) ATT_STORE((ps + 1) & 1);
.LBB0_822:
	s_or_b64 exec, exec, s[14:15]
	s_waitcnt lgkmcnt(0)
	s_nop 0
	v_add_f32_e32 v136, v83, v136
	v_max_f32_e32 v80, v158, v158
	v_max_f32_e32 v80, v80, v136
	ds_bpermute_b32 v81, v147, v80
	s_andn2_b64 vcc, exec, s[10:11]
	s_waitcnt lgkmcnt(0)
	v_max_f32_e32 v81, v81, v81
	v_max_f32_e32 v80, v80, v81
	ds_bpermute_b32 v81, v109, v80
	s_waitcnt lgkmcnt(0)
	v_max3_f32 v81, v155, v80, v81
	v_sub_f32_e32 v80, v155, v81
	v_sub_f32_e32 v83, v123, v81
	v_sub_f32_e32 v123, v136, v81
	v_add3_u32 v136, s16, v139, v140
	v_exp_f32_e32 v80, v80
	v_sub_f32_e32 v88, v128, v81
	v_sub_f32_e32 v89, v129, v81
	v_sub_f32_e32 v90, v130, v81
	v_sub_f32_e32 v91, v131, v81
	v_sub_f32_e32 v92, v132, v81
	v_sub_f32_e32 v93, v133, v81
	v_sub_f32_e32 v94, v134, v81
	v_sub_f32_e32 v95, v135, v81
	ds_read_b64_tr_b16 v[184:185], v136 offset:34816
	ds_read_b64_tr_b16 v[186:187], v136 offset:39168
	ds_read_b64_tr_b16 v[188:189], v136 offset:34848
	ds_read_b64_tr_b16 v[190:191], v136 offset:39200
	ds_read_b64_tr_b16 v[192:193], v136 offset:34880
	ds_read_b64_tr_b16 v[194:195], v136 offset:39232
	ds_read_b64_tr_b16 v[196:197], v136 offset:34912
	ds_read_b64_tr_b16 v[198:199], v136 offset:39264
	ds_read_b64_tr_b16 v[200:201], v136 offset:34944
	ds_read_b64_tr_b16 v[202:203], v136 offset:39296
	ds_read_b64_tr_b16 v[204:205], v136 offset:34976
	ds_read_b64_tr_b16 v[206:207], v136 offset:39328
	ds_read_b64_tr_b16 v[208:209], v136 offset:35008
	ds_read_b64_tr_b16 v[210:211], v136 offset:39360
	v_sub_f32_e32 v82, v122, v81
	v_sub_f32_e32 v84, v124, v81
	v_sub_f32_e32 v85, v125, v81
	v_sub_f32_e32 v86, v126, v81
	v_sub_f32_e32 v87, v127, v81
	v_pk_mul_f32 v[78:79], v[78:79], v[80:81] op_sel_hi:[1,0]
	v_pk_mul_f32 v[76:77], v[76:77], v[80:81] op_sel_hi:[1,0]
	v_pk_mul_f32 v[74:75], v[74:75], v[80:81] op_sel_hi:[1,0]
	v_pk_mul_f32 v[72:73], v[72:73], v[80:81] op_sel_hi:[1,0]
	v_pk_mul_f32 v[70:71], v[70:71], v[80:81] op_sel_hi:[1,0]
	v_pk_mul_f32 v[68:69], v[68:69], v[80:81] op_sel_hi:[1,0]
	v_pk_mul_f32 v[66:67], v[66:67], v[80:81] op_sel_hi:[1,0]
	v_pk_mul_f32 v[64:65], v[64:65], v[80:81] op_sel_hi:[1,0]
	v_exp_f32_e32 v82, v82
	v_exp_f32_e32 v83, v83
	v_exp_f32_e32 v84, v84
	v_exp_f32_e32 v85, v85
	v_exp_f32_e32 v86, v86
	v_exp_f32_e32 v87, v87
	v_exp_f32_e32 v88, v88
	v_exp_f32_e32 v89, v89
	v_cvt_pk_bf16_f32 v124, v82, v83
	v_cvt_pk_bf16_f32 v125, v84, v85
	v_cvt_pk_bf16_f32 v126, v86, v87
	v_cvt_pk_bf16_f32 v127, v88, v89
	v_pk_mul_f32 v[62:63], v[62:63], v[80:81] op_sel_hi:[1,0]
	s_waitcnt lgkmcnt(12)
	v_mfma_f32_16x16x32_bf16 v[76:79], v[184:187], v[124:127], v[76:79]
	ds_read_b64_tr_b16 v[212:213], v136 offset:35040
	ds_read_b64_tr_b16 v[214:215], v136 offset:39392
	v_pk_mul_f32 v[60:61], v[60:61], v[80:81] op_sel_hi:[1,0]
	v_pk_mul_f32 v[58:59], v[58:59], v[80:81] op_sel_hi:[1,0]
	s_waitcnt lgkmcnt(12)
	v_mfma_f32_16x16x32_bf16 v[72:75], v[188:191], v[124:127], v[72:75]
	ds_read_b64_tr_b16 v[216:217], v136 offset:43520
	ds_read_b64_tr_b16 v[218:219], v136 offset:47872
	v_mul_f32_e64 v56, v56, v80
	v_mul_f32_e64 v57, v57, v80
	v_pk_mul_f32 v[38:39], v[38:39], v[80:81] op_sel_hi:[1,0]
	v_pk_mul_f32 v[36:37], v[36:37], v[80:81] op_sel_hi:[1,0]
	s_waitcnt lgkmcnt(12)
	v_mfma_f32_16x16x32_bf16 v[68:71], v[192:195], v[124:127], v[68:71]
	ds_read_b64_tr_b16 v[220:221], v136 offset:43552
	ds_read_b64_tr_b16 v[222:223], v136 offset:47904
	v_mul_f32_e64 v30, v30, v80
	v_mul_f32_e64 v31, v31, v80
	v_pk_mul_f32 v[28:29], v[28:29], v[80:81] op_sel_hi:[1,0]
	v_sub_f32_e32 v122, v157, v81
	s_waitcnt lgkmcnt(12)
	v_mfma_f32_16x16x32_bf16 v[64:67], v[196:199], v[124:127], v[64:67]
	ds_read_b64_tr_b16 v[224:225], v136 offset:43584
	ds_read_b64_tr_b16 v[226:227], v136 offset:47936
	v_exp_f32_e32 v90, v90
	v_exp_f32_e32 v91, v91
	s_waitcnt lgkmcnt(12)
	v_mfma_f32_16x16x32_bf16 v[60:63], v[200:203], v[124:127], v[60:63]
	ds_read_b64_tr_b16 v[228:229], v136 offset:43616
	ds_read_b64_tr_b16 v[230:231], v136 offset:47968
	v_exp_f32_e32 v92, v92
	v_exp_f32_e32 v93, v93
	v_exp_f32_e32 v94, v94
	s_waitcnt lgkmcnt(12)
	v_mfma_f32_16x16x32_bf16 v[56:59], v[204:207], v[124:127], v[56:59]
	ds_read_b64_tr_b16 v[232:233], v136 offset:43648
	ds_read_b64_tr_b16 v[234:235], v136 offset:48000
	v_exp_f32_e32 v95, v95
	v_exp_f32_e32 v122, v122
	s_waitcnt lgkmcnt(12)
	v_mfma_f32_16x16x32_bf16 v[36:39], v[208:211], v[124:127], v[36:39]
	ds_read_b64_tr_b16 v[236:237], v136 offset:43680
	ds_read_b64_tr_b16 v[238:239], v136 offset:48032
	v_exp_f32_e32 v123, v123
	v_cvt_pk_bf16_f32 v128, v90, v91
	v_cvt_pk_bf16_f32 v129, v92, v93
	s_waitcnt lgkmcnt(12)
	v_mfma_f32_16x16x32_bf16 v[28:31], v[212:215], v[124:127], v[28:31]
	ds_read_b64_tr_b16 v[240:241], v136 offset:43712
	ds_read_b64_tr_b16 v[242:243], v136 offset:48064
	v_cvt_pk_bf16_f32 v130, v94, v95
	v_cvt_pk_bf16_f32 v131, v122, v123
	s_nop 1
	s_waitcnt lgkmcnt(12)
	v_mfma_f32_16x16x32_bf16 v[76:79], v[216:219], v[128:131], v[76:79]
	ds_read_b64_tr_b16 v[172:173], v136 offset:43744
	ds_read_b64_tr_b16 v[174:175], v136 offset:48096
	s_waitcnt lgkmcnt(12)
	v_mfma_f32_16x16x32_bf16 v[72:75], v[220:223], v[128:131], v[72:75]
	s_waitcnt lgkmcnt(10)
	v_mfma_f32_16x16x32_bf16 v[68:71], v[224:227], v[128:131], v[68:71]
	s_waitcnt lgkmcnt(8)
	v_mfma_f32_16x16x32_bf16 v[64:67], v[228:231], v[128:131], v[64:67]
	s_waitcnt lgkmcnt(6)
	v_mfma_f32_16x16x32_bf16 v[60:63], v[232:235], v[128:131], v[60:63]
	s_waitcnt lgkmcnt(4)
	v_mfma_f32_16x16x32_bf16 v[56:59], v[236:239], v[128:131], v[56:59]
	s_waitcnt lgkmcnt(2)
	v_mfma_f32_16x16x32_bf16 v[36:39], v[240:243], v[128:131], v[36:39]
	s_waitcnt lgkmcnt(0)
	v_mfma_f32_16x16x32_bf16 v[28:31], v[172:175], v[128:131], v[28:31]
	s_cbranch_vccnz .LBB0_824
	s_andn2_b32 s10, 1, s8
	s_mul_i32 s10, s10, 0x11000
	v_add_u32_e32 v124, s10, v137
	s_waitcnt vmcnt(0)
	ds_write_b128 v124, v[0:3]
	ds_write_b128 v124, v[8:11] offset:8704
	ds_write_b128 v124, v[4:7] offset:17408
	ds_write_b128 v124, v[16:19] offset:26112
	ds_write_b128 v124, v[12:15] offset:34816
	ds_write_b128 v124, v[24:27] offset:43520
	ds_write_b128 v124, v[20:23] offset:52224
	ds_write_b128 v124, v[32:35] offset:60928

; __global__ void __launch_bounds__(512) mega(Params p) {
	.amdhsa_kernel _Z4mega6Params
		.amdhsa_group_segment_fixed_size 0
		.amdhsa_private_segment_fixed_size 0
		.amdhsa_kernarg_size 536
		.amdhsa_user_sgpr_count 2
		.amdhsa_user_sgpr_dispatch_ptr 0
		.amdhsa_user_sgpr_queue_ptr 0
		.amdhsa_user_sgpr_kernarg_segment_ptr 1
		.amdhsa_user_sgpr_dispatch_id 0
		.amdhsa_user_sgpr_kernarg_preload_length 0
		.amdhsa_user_sgpr_kernarg_preload_offset 0
		.amdhsa_user_sgpr_private_segment_size 0
		.amdhsa_uses_dynamic_stack 0
		.amdhsa_enable_private_segment 0
		.amdhsa_system_sgpr_workgroup_id_x 1
		.amdhsa_system_sgpr_workgroup_id_y 0
		.amdhsa_system_sgpr_workgroup_id_z 0
		.amdhsa_system_sgpr_workgroup_info 0
		.amdhsa_system_vgpr_workitem_id 2
		.amdhsa_next_free_vgpr 248
		.amdhsa_next_free_sgpr 102
		.amdhsa_accum_offset 248
		.amdhsa_reserve_vcc 1
		.amdhsa_float_round_mode_32 0
		.amdhsa_float_round_mode_16_64 0
		.amdhsa_float_denorm_mode_32 3
		.amdhsa_float_denorm_mode_16_64 3
		.amdhsa_dx10_clamp 1
		.amdhsa_ieee_mode 1
		.amdhsa_fp16_overflow 0
		.amdhsa_tg_split 0
		.amdhsa_exception_fp_ieee_invalid_op 0
		.amdhsa_exception_fp_denorm_src 0
		.amdhsa_exception_fp_ieee_div_zero 0
		.amdhsa_exception_fp_ieee_overflow 0
		.amdhsa_exception_fp_ieee_underflow 0
		.amdhsa_exception_fp_ieee_inexact 0
		.amdhsa_exception_int_div_zero 0
	.end_amdhsa_kernel

; __global__ void __launch_bounds__(512) mega(Params p) {
amdhsa.kernels:
  - .agpr_count:     0
    .args:
      - .offset:         0
        .size:           280
        .value_kind:     by_value
      - .offset:         280
        .size:           4
        .value_kind:     hidden_block_count_x
      - .offset:         284
        .size:           4
        .value_kind:     hidden_block_count_y
      - .offset:         288
        .size:           4
        .value_kind:     hidden_block_count_z
      - .offset:         292
        .size:           2
        .value_kind:     hidden_group_size_x
      - .offset:         294
        .size:           2
        .value_kind:     hidden_group_size_y
      - .offset:         296
        .size:           2
        .value_kind:     hidden_group_size_z
      - .offset:         298
        .size:           2
        .value_kind:     hidden_remainder_x
      - .offset:         300
        .size:           2
        .value_kind:     hidden_remainder_y
      - .offset:         302
        .size:           2
        .value_kind:     hidden_remainder_z
      - .offset:         320
        .size:           8
        .value_kind:     hidden_global_offset_x
      - .offset:         328
        .size:           8
        .value_kind:     hidden_global_offset_y
      - .offset:         336
        .size:           8
        .value_kind:     hidden_global_offset_z
      - .offset:         344
        .size:           2
        .value_kind:     hidden_grid_dims
      - .offset:         368
        .size:           8
        .value_kind:     hidden_multigrid_sync_arg
      - .offset:         400
        .size:           4
        .value_kind:     hidden_dynamic_lds_size
    .group_segment_fixed_size: 0
    .kernarg_segment_align: 8
    .kernarg_segment_size: 536
    .language:       OpenCL C
    .language_version:
      - 2
      - 0
    .max_flat_workgroup_size: 512
    .name:           _Z4mega6Params
    .private_segment_fixed_size: 0
    .sgpr_count:     108
    .sgpr_spill_count: 127
    .symbol:         _Z4mega6Params.kd
    .uniform_work_group_size: 1
    .uses_dynamic_stack: false
    .vgpr_count:     248
    .vgpr_spill_count: 0
    .wavefront_size: 64
